# GU K-loop: A0 half-tile DMA moved from SP2 to next SP1 (4/4 DMA balance), vmcnt 8/6
# speedup vs baseline: 1.0050x; 1.0050x over previous
; #define PG8_STAGE(bufoff, gbase, voff) do { _Pragma("unroll") for (int _i = 0; _i < 2; ++_i) \
;         __builtin_amdgcn_global_load_lds((const unsigned*)((const char*)(gbase) + (voff)[_i]), (LAS unsigned*)(lds + (bufoff) + ldsw + _i * 8192), 16, 0, 0); } while (0)
; #define PG8_LDA(dst, b, h) do { _Pragma("unroll") for (int m = 0; m < 4; ++m) _Pragma("unroll") for (int k = 0; k < 2; ++k) dst[m][k] = *(const LAS bf16x8*)(lds + PG8_SA(b, h) + aoff + m * 2048 + k * 1024); } while (0)
; #define PG8_LDB(dst, b, h) do { _Pragma("unroll") for (int n = 0; n < 2; ++n) _Pragma("unroll") for (int k = 0; k < 2; ++k) dst[n][k] = *(const LAS bf16x8*)(lds + PG8_SB(b, h) + boff + n * 2048 + k * 1024); } while (0)
; #define PG8_MMA(ai, bj, At, Bt) do { __builtin_amdgcn_s_setprio(1); _Pragma("unroll") for (int m = 0; m < 4; ++m) _Pragma("unroll") for (int n = 0; n < 2; ++n) _Pragma("unroll") for (int k = 0; k < 2; ++k) \
;         acc[ai][bj][m][n] = __builtin_amdgcn_mfma_f32_16x16x32_bf16(Bt[n][k], At[m][k], acc[ai][bj][m][n], 0, 0, 0); __builtin_amdgcn_s_setprio(0); } while (0)
; #define PG8_WAIT_V(n) asm volatile("s_waitcnt vmcnt(" #n ")" ::: "memory")
; #define PG8_WAIT_L(n) asm volatile("s_waitcnt lgkmcnt(" #n ")" ::: "memory")
; #define PG8_BAR __builtin_amdgcn_s_barrier()
; #define PG8_SCHED __builtin_amdgcn_sched_barrier(0)
; template <class Epi, class Sched>
; __device__ __forceinline__ void gemm_phase(LAS unsigned char* lds, const Gemm g, const Sched& S, const Epi& E, const int tid) {
;     ...
;         for (int t = 0; t < nt; t += 2) {
;             const bool last = (t == nt - 2);
;             const char* a1 = cA + (size_t)(t + 1) * kstep;
;             const char* a2 = last ? nA : cA + (size_t)(t + 2) * kstep; const char* b2 = last ? nB : cB + (size_t)(t + 2) * kstep;
;             const char* a3 = a2 + kstep; const char* b3 = b2 + kstep;
;             PG8_LDB(B0, 0, 0); PG8_LDB(B1, 0, 1); PG8_SCHED; PG8_LDA(At, 0, 0); PG8_STAGE(PG8_SA(1, 1), a1 + hstep, voffA);
;             PG8_WAIT_V(8); PG8_WAIT_L(0); PG8_BAR; PG8_MMA(0, 0, At, B0); PG8_MMA(0, 1, At, B1); PG8_BAR; PG8_SCHED;
;             PG8_LDA(At, 0, 1); PG8_STAGE(PG8_SB(0, 0), b2, voffB); PG8_STAGE(PG8_SB(0, 1), b2 + hstep, voffB); PG8_STAGE(PG8_SA(0, 0), a2, voffA);
;             PG8_WAIT_V(8); PG8_WAIT_L(0); PG8_BAR; PG8_MMA(1, 0, At, B0); PG8_MMA(1, 1, At, B1); PG8_BAR; PG8_SCHED;
.LBB0_168:
	s_add_u32 s63, s64, 0xfffc0080
	s_addc_u32 s66, s65, -1
	s_add_i32 s78, 0, 0x10000
	s_cmp_eq_u32 s61, 12
	s_cselect_b32 s71, s55, s66
	s_cselect_b32 s70, s56, s63
	v_add_u32_e32 v145, s78, v166
	s_cselect_b32 s67, s57, s60
	s_cselect_b32 s66, s58, s59
	s_add_i32 s63, 0, 0x14000
	s_add_u32 s100, s64, 0xfffc0000
	s_addc_u32 s101, s65, -1
	ds_read_b128 v[146:149], v145
	ds_read_b128 v[150:153], v145 offset:1024
	ds_read_b128 v[154:157], v145 offset:2048
	ds_read_b128 v[158:161], v145 offset:3072
	v_add_u32_e32 v145, s63, v166
	ds_read_b128 v[172:175], v145
	ds_read_b128 v[176:179], v145 offset:1024
	ds_read_b128 v[180:183], v145 offset:2048
	ds_read_b128 v[184:187], v145 offset:3072
	v_lshl_add_u64 v[236:237], s[100:101], 0, v[138:139]
	v_lshl_add_u64 v[238:239], s[100:101], 0, v[136:137]
	v_lshl_add_u64 v[162:163], s[64:65], 0, v[140:141]
	s_mov_b32 m0, s93
	ds_read_b128 v[188:191], v171
	ds_read_b128 v[198:201], v171 offset:1024
	ds_read_b128 v[202:205], v171 offset:2048
	ds_read_b128 v[206:209], v171 offset:3072
	ds_read_b128 v[210:213], v171 offset:4096
	ds_read_b128 v[214:217], v171 offset:5120
	ds_read_b128 v[218:221], v171 offset:6144
	ds_read_b128 v[230:233], v171 offset:7168
	global_load_lds_dwordx4 v[236:237], off
	s_mov_b32 m0, s94
	v_lshl_add_u64 v[236:237], s[64:65], 0, v[142:143]
	global_load_lds_dwordx4 v[238:239], off
	s_add_i32 m0, s75, 0xc000
	s_nop 0
	global_load_lds_dwordx4 v[162:163], off
	s_add_i32 m0, s75, 0xe000
	s_nop 0
	global_load_lds_dwordx4 v[236:237], off
	s_waitcnt vmcnt(8)
	s_waitcnt lgkmcnt(0)
	s_barrier
	s_setprio 1
	s_waitcnt lgkmcnt(0)
	v_mfma_f32_16x16x32_bf16 v[128:131], v[146:149], v[188:191], v[128:131]
	v_mfma_f32_16x16x32_bf16 v[124:127], v[154:157], v[188:191], v[124:127]
	v_mfma_f32_16x16x32_bf16 v[108:111], v[146:149], v[202:205], v[108:111]
	v_mfma_f32_16x16x32_bf16 v[104:107], v[154:157], v[202:205], v[104:107]
	v_mfma_f32_16x16x32_bf16 v[92:95], v[146:149], v[210:213], v[92:95]
	v_mfma_f32_16x16x32_bf16 v[88:91], v[154:157], v[210:213], v[88:91]
	v_mfma_f32_16x16x32_bf16 v[76:79], v[146:149], v[218:221], v[76:79]
	v_mfma_f32_16x16x32_bf16 v[72:75], v[154:157], v[218:221], v[72:75]
	v_mfma_f32_16x16x32_bf16 v[128:131], v[150:153], v[198:201], v[128:131]
	v_mfma_f32_16x16x32_bf16 v[124:127], v[158:161], v[198:201], v[124:127]
	v_mfma_f32_16x16x32_bf16 v[108:111], v[150:153], v[206:209], v[108:111]
	v_mfma_f32_16x16x32_bf16 v[104:107], v[158:161], v[206:209], v[104:107]
	v_mfma_f32_16x16x32_bf16 v[92:95], v[150:153], v[214:217], v[92:95]
	v_mfma_f32_16x16x32_bf16 v[88:91], v[158:161], v[214:217], v[88:91]
	v_mfma_f32_16x16x32_bf16 v[76:79], v[150:153], v[230:233], v[76:79]
	v_mfma_f32_16x16x32_bf16 v[72:75], v[158:161], v[230:233], v[72:75]
	s_setprio 0
	s_setprio 1
	v_mfma_f32_16x16x32_bf16 v[120:123], v[172:175], v[188:191], v[120:123]
	v_mfma_f32_16x16x32_bf16 v[116:119], v[180:183], v[188:191], v[116:119]
	v_mfma_f32_16x16x32_bf16 v[100:103], v[172:175], v[202:205], v[100:103]
	v_mfma_f32_16x16x32_bf16 v[96:99], v[180:183], v[202:205], v[96:99]
	v_mfma_f32_16x16x32_bf16 v[84:87], v[172:175], v[210:213], v[84:87]
	v_mfma_f32_16x16x32_bf16 v[80:83], v[180:183], v[210:213], v[80:83]
	v_mfma_f32_16x16x32_bf16 v[68:71], v[172:175], v[218:221], v[68:71]
	v_mfma_f32_16x16x32_bf16 v[64:67], v[180:183], v[218:221], v[64:67]
	v_mfma_f32_16x16x32_bf16 v[120:123], v[176:179], v[198:201], v[120:123]
	v_mfma_f32_16x16x32_bf16 v[116:119], v[184:187], v[198:201], v[116:119]
	v_mfma_f32_16x16x32_bf16 v[100:103], v[176:179], v[206:209], v[100:103]
	v_mfma_f32_16x16x32_bf16 v[96:99], v[184:187], v[206:209], v[96:99]
	v_mfma_f32_16x16x32_bf16 v[84:87], v[176:179], v[214:217], v[84:87]
	v_mfma_f32_16x16x32_bf16 v[80:83], v[184:187], v[214:217], v[80:83]
	v_mfma_f32_16x16x32_bf16 v[68:71], v[176:179], v[230:233], v[68:71]
	v_mfma_f32_16x16x32_bf16 v[64:67], v[184:187], v[230:233], v[64:67]
	s_setprio 0
	s_barrier
	s_add_i32 s78, s78, s74
	v_lshl_add_u64 v[162:163], s[66:67], 0, v[192:193]
	s_mov_b32 m0, s78
	ds_read_b128 v[188:191], v171 offset:16384
	ds_read_b128 v[198:201], v171 offset:17408
	ds_read_b128 v[202:205], v171 offset:18432
	ds_read_b128 v[206:209], v171 offset:19456
	ds_read_b128 v[210:213], v171 offset:20480
	ds_read_b128 v[214:217], v171 offset:21504
	ds_read_b128 v[218:221], v171 offset:22528
	ds_read_b128 v[230:233], v171 offset:23552
	global_load_lds_dwordx4 v[162:163], off
	s_add_i32 m0, s78, 0x2000
	s_add_u32 s78, s66, 0x40000
	v_lshl_add_u64 v[234:235], s[66:67], 0, v[134:135]
	s_addc_u32 s79, s67, 0
	s_add_i32 s63, s63, s74
	global_load_lds_dwordx4 v[234:235], off
	v_lshl_add_u64 v[236:237], s[78:79], 0, v[192:193]
	s_mov_b32 m0, s63
	s_nop 0
	global_load_lds_dwordx4 v[236:237], off
	v_lshl_add_u64 v[236:237], s[78:79], 0, v[134:135]
	s_add_i32 m0, s63, 0x2000
	s_nop 0
	global_load_lds_dwordx4 v[236:237], off
	s_waitcnt vmcnt(6)
	s_waitcnt lgkmcnt(0)
	s_barrier
; #define PG8_STAGE(bufoff, gbase, voff) do { _Pragma("unroll") for (int _i = 0; _i < 2; ++_i) \
;         __builtin_amdgcn_global_load_lds((const unsigned*)((const char*)(gbase) + (voff)[_i]), (LAS unsigned*)(lds + (bufoff) + ldsw + _i * 8192), 16, 0, 0); } while (0)
; #define PG8_LDA(dst, b, h) do { _Pragma("unroll") for (int m = 0; m < 4; ++m) _Pragma("unroll") for (int k = 0; k < 2; ++k) dst[m][k] = *(const LAS bf16x8*)(lds + PG8_SA(b, h) + aoff + m * 2048 + k * 1024); } while (0)
; #define PG8_LDB(dst, b, h) do { _Pragma("unroll") for (int n = 0; n < 2; ++n) _Pragma("unroll") for (int k = 0; k < 2; ++k) dst[n][k] = *(const LAS bf16x8*)(lds + PG8_SB(b, h) + boff + n * 2048 + k * 1024); } while (0)
; #define PG8_MMA(ai, bj, At, Bt) do { __builtin_amdgcn_s_setprio(1); _Pragma("unroll") for (int m = 0; m < 4; ++m) _Pragma("unroll") for (int n = 0; n < 2; ++n) _Pragma("unroll") for (int k = 0; k < 2; ++k) \
;         acc[ai][bj][m][n] = __builtin_amdgcn_mfma_f32_16x16x32_bf16(Bt[n][k], At[m][k], acc[ai][bj][m][n], 0, 0, 0); __builtin_amdgcn_s_setprio(0); } while (0)
; #define PG8_WAIT_V(n) asm volatile("s_waitcnt vmcnt(" #n ")" ::: "memory")
; #define PG8_WAIT_L(n) asm volatile("s_waitcnt lgkmcnt(" #n ")" ::: "memory")
; #define PG8_BAR __builtin_amdgcn_s_barrier()
; #define PG8_SCHED __builtin_amdgcn_sched_barrier(0)
; template <class Epi, class Sched>
; __device__ __forceinline__ void gemm_phase(LAS unsigned char* lds, const Gemm g, const Sched& S, const Epi& E, const int tid) {
;     ...
;             PG8_WAIT_V(8); PG8_WAIT_L(0); PG8_BAR; PG8_MMA(1, 0, At, B0); PG8_MMA(1, 1, At, B1); PG8_BAR; PG8_SCHED;
;             PG8_LDB(B0, 1, 0); PG8_LDB(B1, 1, 1); PG8_SCHED; PG8_LDA(At, 1, 0); PG8_STAGE(PG8_SA(0, 1), a2 + hstep, voffA);
;             PG8_WAIT_V(8); PG8_WAIT_L(0); PG8_BAR; PG8_MMA(0, 0, At, B0); PG8_MMA(0, 1, At, B1); PG8_BAR; PG8_SCHED;
	s_setprio 1
	s_waitcnt lgkmcnt(0)
	v_mfma_f32_16x16x32_bf16 v[60:63], v[146:149], v[188:191], v[60:63]
	v_mfma_f32_16x16x32_bf16 v[56:59], v[154:157], v[188:191], v[56:59]
	v_mfma_f32_16x16x32_bf16 v[44:47], v[146:149], v[202:205], v[44:47]
	v_mfma_f32_16x16x32_bf16 v[40:43], v[154:157], v[202:205], v[40:43]
	v_mfma_f32_16x16x32_bf16 v[28:31], v[146:149], v[210:213], v[28:31]
	v_mfma_f32_16x16x32_bf16 v[24:27], v[154:157], v[210:213], v[24:27]
	v_mfma_f32_16x16x32_bf16 v[12:15], v[146:149], v[218:221], v[12:15]
	v_mfma_f32_16x16x32_bf16 v[8:11], v[154:157], v[218:221], v[8:11]
	v_mfma_f32_16x16x32_bf16 v[60:63], v[150:153], v[198:201], v[60:63]
	v_mfma_f32_16x16x32_bf16 v[56:59], v[158:161], v[198:201], v[56:59]
	v_mfma_f32_16x16x32_bf16 v[44:47], v[150:153], v[206:209], v[44:47]
	v_mfma_f32_16x16x32_bf16 v[40:43], v[158:161], v[206:209], v[40:43]
	v_mfma_f32_16x16x32_bf16 v[28:31], v[150:153], v[214:217], v[28:31]
	v_mfma_f32_16x16x32_bf16 v[24:27], v[158:161], v[214:217], v[24:27]
	v_mfma_f32_16x16x32_bf16 v[12:15], v[150:153], v[230:233], v[12:15]
	v_mfma_f32_16x16x32_bf16 v[8:11], v[158:161], v[230:233], v[8:11]
	s_setprio 0
	s_setprio 1
	v_mfma_f32_16x16x32_bf16 v[52:55], v[172:175], v[188:191], v[52:55]
	v_mfma_f32_16x16x32_bf16 v[48:51], v[180:183], v[188:191], v[48:51]
	v_mfma_f32_16x16x32_bf16 v[36:39], v[172:175], v[202:205], v[36:39]
	v_mfma_f32_16x16x32_bf16 v[32:35], v[180:183], v[202:205], v[32:35]
	v_mfma_f32_16x16x32_bf16 v[20:23], v[172:175], v[210:213], v[20:23]
	v_mfma_f32_16x16x32_bf16 v[16:19], v[180:183], v[210:213], v[16:19]
	v_mfma_f32_16x16x32_bf16 v[4:7], v[172:175], v[218:221], v[4:7]
	v_mfma_f32_16x16x32_bf16 v[0:3], v[180:183], v[218:221], v[0:3]
	v_mfma_f32_16x16x32_bf16 v[52:55], v[176:179], v[198:201], v[52:55]
	v_mfma_f32_16x16x32_bf16 v[48:51], v[184:187], v[198:201], v[48:51]
	v_mfma_f32_16x16x32_bf16 v[36:39], v[176:179], v[206:209], v[36:39]
	v_mfma_f32_16x16x32_bf16 v[32:35], v[184:187], v[206:209], v[32:35]
	v_mfma_f32_16x16x32_bf16 v[20:23], v[176:179], v[214:217], v[20:23]
	v_mfma_f32_16x16x32_bf16 v[16:19], v[184:187], v[214:217], v[16:19]
	v_mfma_f32_16x16x32_bf16 v[4:7], v[176:179], v[230:233], v[4:7]
	v_mfma_f32_16x16x32_bf16 v[0:3], v[184:187], v[230:233], v[0:3]
	s_setprio 0
	s_barrier
	s_add_i32 s63, 0, 0x18000
	v_add_u32_e32 v145, s63, v166
	s_add_i32 s78, 0, 0x1c000
	ds_read_b128 v[146:149], v145
	ds_read_b128 v[150:153], v145 offset:1024
	ds_read_b128 v[154:157], v145 offset:2048
	ds_read_b128 v[158:161], v145 offset:3072
	v_add_u32_e32 v145, s78, v166
	ds_read_b128 v[172:175], v145
	ds_read_b128 v[176:179], v145 offset:1024
	ds_read_b128 v[180:183], v145 offset:2048
	ds_read_b128 v[184:187], v145 offset:3072
	v_lshl_add_u64 v[236:237], s[70:71], 0, v[138:139]
	v_lshl_add_u64 v[238:239], s[70:71], 0, v[136:137]
	s_add_u32 s70, s70, 0x40000
	s_addc_u32 s71, s71, 0
	s_mov_b32 m0, s75
	v_lshl_add_u64 v[240:241], s[70:71], 0, v[138:139]
	ds_read_b128 v[188:191], v171 offset:32768
	ds_read_b128 v[198:201], v171 offset:33792
	ds_read_b128 v[202:205], v171 offset:34816
	ds_read_b128 v[206:209], v171 offset:35840
	ds_read_b128 v[210:213], v171 offset:36864
	ds_read_b128 v[214:217], v171 offset:37888
	ds_read_b128 v[218:221], v171 offset:38912
	ds_read_b128 v[230:233], v171 offset:39936
	global_load_lds_dwordx4 v[236:237], off
	s_mov_b32 m0, s81
	s_nop 0
	global_load_lds_dwordx4 v[238:239], off
	s_mov_b32 m0, s82
	s_nop 0
	global_load_lds_dwordx4 v[240:241], off
	v_lshl_add_u64 v[240:241], s[70:71], 0, v[136:137]
	s_mov_b32 m0, s83
	s_nop 0
	global_load_lds_dwordx4 v[240:241], off
	s_waitcnt vmcnt(8)
	s_waitcnt lgkmcnt(0)
	s_barrier
; #define PG8_STAGE(bufoff, gbase, voff) do { _Pragma("unroll") for (int _i = 0; _i < 2; ++_i) \
;         __builtin_amdgcn_global_load_lds((const unsigned*)((const char*)(gbase) + (voff)[_i]), (LAS unsigned*)(lds + (bufoff) + ldsw + _i * 8192), 16, 0, 0); } while (0)
; #define PG8_LDA(dst, b, h) do { _Pragma("unroll") for (int m = 0; m < 4; ++m) _Pragma("unroll") for (int k = 0; k < 2; ++k) dst[m][k] = *(const LAS bf16x8*)(lds + PG8_SA(b, h) + aoff + m * 2048 + k * 1024); } while (0)
; #define PG8_MMA(ai, bj, At, Bt) do { __builtin_amdgcn_s_setprio(1); _Pragma("unroll") for (int m = 0; m < 4; ++m) _Pragma("unroll") for (int n = 0; n < 2; ++n) _Pragma("unroll") for (int k = 0; k < 2; ++k) \
;         acc[ai][bj][m][n] = __builtin_amdgcn_mfma_f32_16x16x32_bf16(Bt[n][k], At[m][k], acc[ai][bj][m][n], 0, 0, 0); __builtin_amdgcn_s_setprio(0); } while (0)
; #define PG8_WAIT_V(n) asm volatile("s_waitcnt vmcnt(" #n ")" ::: "memory")
; #define PG8_WAIT_L(n) asm volatile("s_waitcnt lgkmcnt(" #n ")" ::: "memory")
; #define PG8_BAR __builtin_amdgcn_s_barrier()
; #define PG8_SCHED __builtin_amdgcn_sched_barrier(0)
; template <class Epi, class Sched>
; __device__ __forceinline__ void gemm_phase(LAS unsigned char* lds, const Gemm g, const Sched& S, const Epi& E, const int tid) {
;     ...
;             PG8_WAIT_V(8); PG8_WAIT_L(0); PG8_BAR; PG8_MMA(0, 0, At, B0); PG8_MMA(0, 1, At, B1); PG8_BAR; PG8_SCHED;
;             PG8_LDA(At, 1, 1); PG8_STAGE(PG8_SB(1, 0), b3, voffB); PG8_STAGE(PG8_SB(1, 1), b3 + hstep, voffB); PG8_STAGE(PG8_SA(1, 0), a3, voffA);
;             PG8_WAIT_V(8); PG8_WAIT_L(0); PG8_BAR; PG8_MMA(1, 0, At, B0); PG8_MMA(1, 1, At, B1); PG8_BAR; PG8_SCHED;
;         }
;         if (wr == 0) PG8_BAR;
	s_setprio 1
	s_waitcnt lgkmcnt(0)
	v_mfma_f32_16x16x32_bf16 v[128:131], v[146:149], v[188:191], v[128:131]
	v_mfma_f32_16x16x32_bf16 v[124:127], v[154:157], v[188:191], v[124:127]
	v_mfma_f32_16x16x32_bf16 v[108:111], v[146:149], v[202:205], v[108:111]
	v_mfma_f32_16x16x32_bf16 v[104:107], v[154:157], v[202:205], v[104:107]
	v_mfma_f32_16x16x32_bf16 v[92:95], v[146:149], v[210:213], v[92:95]
	v_mfma_f32_16x16x32_bf16 v[88:91], v[154:157], v[210:213], v[88:91]
	v_mfma_f32_16x16x32_bf16 v[76:79], v[146:149], v[218:221], v[76:79]
	v_mfma_f32_16x16x32_bf16 v[72:75], v[154:157], v[218:221], v[72:75]
	v_mfma_f32_16x16x32_bf16 v[128:131], v[150:153], v[198:201], v[128:131]
	v_mfma_f32_16x16x32_bf16 v[124:127], v[158:161], v[198:201], v[124:127]
	v_mfma_f32_16x16x32_bf16 v[108:111], v[150:153], v[206:209], v[108:111]
	v_mfma_f32_16x16x32_bf16 v[104:107], v[158:161], v[206:209], v[104:107]
	v_mfma_f32_16x16x32_bf16 v[92:95], v[150:153], v[214:217], v[92:95]
	v_mfma_f32_16x16x32_bf16 v[88:91], v[158:161], v[214:217], v[88:91]
	v_mfma_f32_16x16x32_bf16 v[76:79], v[150:153], v[230:233], v[76:79]
	v_mfma_f32_16x16x32_bf16 v[72:75], v[158:161], v[230:233], v[72:75]
	s_setprio 0
	s_setprio 1
	v_mfma_f32_16x16x32_bf16 v[120:123], v[172:175], v[188:191], v[120:123]
	v_mfma_f32_16x16x32_bf16 v[116:119], v[180:183], v[188:191], v[116:119]
	v_mfma_f32_16x16x32_bf16 v[100:103], v[172:175], v[202:205], v[100:103]
	v_mfma_f32_16x16x32_bf16 v[96:99], v[180:183], v[202:205], v[96:99]
	v_mfma_f32_16x16x32_bf16 v[84:87], v[172:175], v[210:213], v[84:87]
	v_mfma_f32_16x16x32_bf16 v[80:83], v[180:183], v[210:213], v[80:83]
	v_mfma_f32_16x16x32_bf16 v[68:71], v[172:175], v[218:221], v[68:71]
	v_mfma_f32_16x16x32_bf16 v[64:67], v[180:183], v[218:221], v[64:67]
	v_mfma_f32_16x16x32_bf16 v[120:123], v[176:179], v[198:201], v[120:123]
	v_mfma_f32_16x16x32_bf16 v[116:119], v[184:187], v[198:201], v[116:119]
	v_mfma_f32_16x16x32_bf16 v[100:103], v[176:179], v[206:209], v[100:103]
	v_mfma_f32_16x16x32_bf16 v[96:99], v[184:187], v[206:209], v[96:99]
	v_mfma_f32_16x16x32_bf16 v[84:87], v[176:179], v[214:217], v[84:87]
	v_mfma_f32_16x16x32_bf16 v[80:83], v[184:187], v[214:217], v[80:83]
	v_mfma_f32_16x16x32_bf16 v[68:71], v[176:179], v[230:233], v[68:71]
	v_mfma_f32_16x16x32_bf16 v[64:67], v[184:187], v[230:233], v[64:67]
	s_setprio 0
	s_barrier
	s_add_i32 s63, s63, s74
	v_lshl_add_u64 v[162:163], v[162:163], 0, s[68:69]
	s_mov_b32 m0, s63
	ds_read_b128 v[188:191], v171 offset:49152
	ds_read_b128 v[198:201], v171 offset:50176
	ds_read_b128 v[202:205], v171 offset:51200
	ds_read_b128 v[206:209], v171 offset:52224
	ds_read_b128 v[210:213], v171 offset:53248
	ds_read_b128 v[214:217], v171 offset:54272
	ds_read_b128 v[218:221], v171 offset:55296
	ds_read_b128 v[230:233], v171 offset:56320
	global_load_lds_dwordx4 v[162:163], off
	s_add_i32 m0, s63, 0x2000
	s_add_u32 s66, s66, 0x40080
	v_lshl_add_u64 v[162:163], v[234:235], 0, s[68:69]
	s_addc_u32 s67, s67, 0
	s_add_i32 s63, s78, s74
	global_load_lds_dwordx4 v[162:163], off
	v_lshl_add_u64 v[162:163], s[66:67], 0, v[192:193]
	s_mov_b32 m0, s63
	s_nop 0
	global_load_lds_dwordx4 v[162:163], off
	v_lshl_add_u64 v[162:163], s[66:67], 0, v[134:135]
	s_add_i32 m0, s63, 0x2000
	s_nop 0
	global_load_lds_dwordx4 v[162:163], off
	s_waitcnt vmcnt(6)
	s_waitcnt lgkmcnt(0)
	s_barrier
	s_setprio 1
	s_waitcnt lgkmcnt(0)
	v_mfma_f32_16x16x32_bf16 v[60:63], v[146:149], v[188:191], v[60:63]
	v_mfma_f32_16x16x32_bf16 v[56:59], v[154:157], v[188:191], v[56:59]
	v_mfma_f32_16x16x32_bf16 v[44:47], v[146:149], v[202:205], v[44:47]
	v_mfma_f32_16x16x32_bf16 v[40:43], v[154:157], v[202:205], v[40:43]
	v_mfma_f32_16x16x32_bf16 v[28:31], v[146:149], v[210:213], v[28:31]
	v_mfma_f32_16x16x32_bf16 v[24:27], v[154:157], v[210:213], v[24:27]
	v_mfma_f32_16x16x32_bf16 v[12:15], v[146:149], v[218:221], v[12:15]
	v_mfma_f32_16x16x32_bf16 v[8:11], v[154:157], v[218:221], v[8:11]
	v_mfma_f32_16x16x32_bf16 v[60:63], v[150:153], v[198:201], v[60:63]
	v_mfma_f32_16x16x32_bf16 v[56:59], v[158:161], v[198:201], v[56:59]
	v_mfma_f32_16x16x32_bf16 v[44:47], v[150:153], v[206:209], v[44:47]
	v_mfma_f32_16x16x32_bf16 v[40:43], v[158:161], v[206:209], v[40:43]
	v_mfma_f32_16x16x32_bf16 v[28:31], v[150:153], v[214:217], v[28:31]
	v_mfma_f32_16x16x32_bf16 v[24:27], v[158:161], v[214:217], v[24:27]
	v_mfma_f32_16x16x32_bf16 v[12:15], v[150:153], v[230:233], v[12:15]
	v_mfma_f32_16x16x32_bf16 v[8:11], v[158:161], v[230:233], v[8:11]
	s_setprio 0
	s_setprio 1
	v_mfma_f32_16x16x32_bf16 v[52:55], v[172:175], v[188:191], v[52:55]
	v_mfma_f32_16x16x32_bf16 v[48:51], v[180:183], v[188:191], v[48:51]
	v_mfma_f32_16x16x32_bf16 v[36:39], v[172:175], v[202:205], v[36:39]
	v_mfma_f32_16x16x32_bf16 v[32:35], v[180:183], v[202:205], v[32:35]
	v_mfma_f32_16x16x32_bf16 v[20:23], v[172:175], v[210:213], v[20:23]
	v_mfma_f32_16x16x32_bf16 v[16:19], v[180:183], v[210:213], v[16:19]
	v_mfma_f32_16x16x32_bf16 v[4:7], v[172:175], v[218:221], v[4:7]
	v_mfma_f32_16x16x32_bf16 v[0:3], v[180:183], v[218:221], v[0:3]
	v_mfma_f32_16x16x32_bf16 v[52:55], v[176:179], v[198:201], v[52:55]
	v_mfma_f32_16x16x32_bf16 v[48:51], v[184:187], v[198:201], v[48:51]
	v_mfma_f32_16x16x32_bf16 v[36:39], v[176:179], v[206:209], v[36:39]
	v_mfma_f32_16x16x32_bf16 v[32:35], v[184:187], v[206:209], v[32:35]
	v_mfma_f32_16x16x32_bf16 v[20:23], v[176:179], v[214:217], v[20:23]
	v_mfma_f32_16x16x32_bf16 v[16:19], v[184:187], v[214:217], v[16:19]
	v_mfma_f32_16x16x32_bf16 v[4:7], v[176:179], v[230:233], v[4:7]
	v_mfma_f32_16x16x32_bf16 v[0:3], v[184:187], v[230:233], v[0:3]
	s_setprio 0
	s_barrier
	s_add_i32 s61, s61, 2
	s_add_u32 s64, s64, 0x100
	s_addc_u32 s65, s65, 0
	s_add_u32 s59, s59, 0x100
	s_addc_u32 s60, s60, 0
	s_cmp_gt_u32 s61, 13
	s_cbranch_scc0 .LBB0_168
	s_and_b64 vcc, exec, s[50:51]
	s_cbranch_vccz .LBB0_171
	s_barrier

; __global__ void __launch_bounds__(512, 2) fwd_kernel(Args a) {
	.amdhsa_kernel _Z10fwd_kernel4Args
		.amdhsa_group_segment_fixed_size 0
		.amdhsa_private_segment_fixed_size 0
		.amdhsa_kernarg_size 440
		.amdhsa_user_sgpr_count 2
		.amdhsa_user_sgpr_dispatch_ptr 0
		.amdhsa_user_sgpr_queue_ptr 0
		.amdhsa_user_sgpr_kernarg_segment_ptr 1
		.amdhsa_user_sgpr_dispatch_id 0
		.amdhsa_user_sgpr_kernarg_preload_length 0
		.amdhsa_user_sgpr_kernarg_preload_offset 0
		.amdhsa_user_sgpr_private_segment_size 0
		.amdhsa_uses_dynamic_stack 0
		.amdhsa_enable_private_segment 0
		.amdhsa_system_sgpr_workgroup_id_x 1
		.amdhsa_system_sgpr_workgroup_id_y 0
		.amdhsa_system_sgpr_workgroup_id_z 0
		.amdhsa_system_sgpr_workgroup_info 0
		.amdhsa_system_vgpr_workitem_id 2
		.amdhsa_next_free_vgpr 256
		.amdhsa_next_free_sgpr 102
		.amdhsa_accum_offset 256
		.amdhsa_reserve_vcc 1
		.amdhsa_float_round_mode_32 0
		.amdhsa_float_round_mode_16_64 0
		.amdhsa_float_denorm_mode_32 3
		.amdhsa_float_denorm_mode_16_64 3
		.amdhsa_dx10_clamp 1
		.amdhsa_ieee_mode 1
		.amdhsa_fp16_overflow 0
		.amdhsa_tg_split 0
		.amdhsa_exception_fp_ieee_invalid_op 0
		.amdhsa_exception_fp_denorm_src 0
		.amdhsa_exception_fp_ieee_div_zero 0
		.amdhsa_exception_fp_ieee_overflow 0
		.amdhsa_exception_fp_ieee_underflow 0
		.amdhsa_exception_fp_ieee_inexact 0
		.amdhsa_exception_int_div_zero 0
	.end_amdhsa_kernel

; __global__ void __launch_bounds__(512, 2) fwd_kernel(Args a) {
amdhsa.kernels:
  - .agpr_count:     0
    .args:
      - .offset:         0
        .size:           184
        .value_kind:     by_value
      - .offset:         184
        .size:           4
        .value_kind:     hidden_block_count_x
      - .offset:         188
        .size:           4
        .value_kind:     hidden_block_count_y
      - .offset:         192
        .size:           4
        .value_kind:     hidden_block_count_z
      - .offset:         196
        .size:           2
        .value_kind:     hidden_group_size_x
      - .offset:         198
        .size:           2
        .value_kind:     hidden_group_size_y
      - .offset:         200
        .size:           2
        .value_kind:     hidden_group_size_z
      - .offset:         202
        .size:           2
        .value_kind:     hidden_remainder_x
      - .offset:         204
        .size:           2
        .value_kind:     hidden_remainder_y
      - .offset:         206
        .size:           2
        .value_kind:     hidden_remainder_z
      - .offset:         224
        .size:           8
        .value_kind:     hidden_global_offset_x
      - .offset:         232
        .size:           8
        .value_kind:     hidden_global_offset_y
      - .offset:         240
        .size:           8
        .value_kind:     hidden_global_offset_z
      - .offset:         248
        .size:           2
        .value_kind:     hidden_grid_dims
      - .offset:         272
        .size:           8
        .value_kind:     hidden_multigrid_sync_arg
      - .offset:         304
        .size:           4
        .value_kind:     hidden_dynamic_lds_size
    .group_segment_fixed_size: 0
    .kernarg_segment_align: 8
    .kernarg_segment_size: 440
    .language:       OpenCL C
    .language_version:
      - 2
      - 0
    .max_flat_workgroup_size: 512
    .name:           _Z10fwd_kernel4Args
    .private_segment_fixed_size: 0
    .sgpr_count:     108
    .sgpr_spill_count: 211
    .symbol:         _Z10fwd_kernel4Args.kd
    .uniform_work_group_size: 1
    .uses_dynamic_stack: false
    .vgpr_count:     256
    .vgpr_spill_count: 0
    .wavefront_size: 64
